# v81 with the younger half-workgroup's softmax one priority level above the older half's (A: loads 0 / softmax 1 / MFMA 3, B: 0 / 2 / 3) - static raise for the younger half, sec 7.4
# speedup vs baseline: 1.0069x; 1.0006x over previous
; DI void expsum(f32x16& p, float& l_reg, bf16x8& pa0, bf16x8& pa1) {
; #pragma unroll
;     for (int r = 0; r < 16; ++r) p[r] = __builtin_amdgcn_exp2f(p[r]);
;     float ps = 0.f;
; #pragma unroll
;     for (int r = 0; r < 16; ++r) ps += p[r];
;     l_reg += ps; asm volatile("" : "+v"(l_reg));
;     ...
;     ATT_PK4(p, 0, pa0); ATT_PK4(p, 8, pa1);
;     ...
; }
; DI int v_rd_base(int lane) { return ((lane & 3) << 3) | (((lane >> 2) & 3) << 6) | (((lane >> 4) & 1) << 5) | (((lane >> 5) & 1) << 8); }
; template <int OFF> DI s16x4 tr_read(int vb) { s16x4 r; asm volatile("ds_read_b64_tr_b16 %0, %1 offset:%2" : "=&v"(r) : "v"(vb), "i"(OFF) : "memory"); return r; }
; template <int H> DI void v_reads(s16x4* vf, int vb) {
;     vf[0] = tr_read<v_rd_off(0, 2 * H, 0)>(vb); vf[1] = tr_read<v_rd_off(0, 2 * H, 1)>(vb); vf[2] = tr_read<v_rd_off(0, 2 * H + 1, 0)>(vb); vf[3] = tr_read<v_rd_off(0, 2 * H + 1, 1)>(vb);
;     vf[4] = tr_read<v_rd_off(1, 2 * H, 0)>(vb); vf[5] = tr_read<v_rd_off(1, 2 * H, 1)>(vb); vf[6] = tr_read<v_rd_off(1, 2 * H + 1, 0)>(vb); vf[7] = tr_read<v_rd_off(1, 2 * H + 1, 1)>(vb);
;     vf[8] = tr_read<v_rd_off(2, 2 * H, 0)>(vb); vf[9] = tr_read<v_rd_off(2, 2 * H, 1)>(vb); vf[10] = tr_read<v_rd_off(2, 2 * H + 1, 0)>(vb); vf[11] = tr_read<v_rd_off(2, 2 * H + 1, 1)>(vb);
;     vf[12] = tr_read<v_rd_off(3, 2 * H, 0)>(vb); vf[13] = tr_read<v_rd_off(3, 2 * H, 1)>(vb); vf[14] = tr_read<v_rd_off(3, 2 * H + 1, 0)>(vb); vf[15] = tr_read<v_rd_off(3, 2 * H + 1, 1)>(vb);
; }
; DI void pv_mma(f32x16* o, const s16x4* vf, bf16x8 pa0, bf16x8 pa1) {
;     ...
; #pragma unroll
;     for (int d0 = 0; d0 < 4; ++d0) {
;         o[d0] = __builtin_amdgcn_mfma_f32_32x32x16_bf16(pa0, ATT_PK(vf[4 * d0], vf[4 * d0 + 1]), o[d0], 0, 0, 0);
;         o[d0] = __builtin_amdgcn_mfma_f32_32x32x16_bf16(pa1, ATT_PK(vf[4 * d0 + 2], vf[4 * d0 + 3]), o[d0], 0, 0, 0); }
;     ...
; }
.Lhw_d0_b_n1922:
	ds_read_b128 v[122:125], v196 offset:4096
	ds_read_b128 v[132:135], v197 offset:4096
	s_lshl_b32 s2, s1, 14
	ds_read_b128 v[136:139], v198 offset:4096
	ds_read_b128 v[140:143], v199 offset:4096
	ds_read_b64_tr_b16 v[144:145], v121 offset:0
	ds_read_b64_tr_b16 v[146:147], v121 offset:0x800
	ds_read_b64_tr_b16 v[148:149], v121 offset:0x1000
	ds_read_b64_tr_b16 v[150:151], v121 offset:0x1800
	ds_read_b64_tr_b16 v[152:153], v121 offset:0x200
	ds_read_b64_tr_b16 v[154:155], v121 offset:0xa00
	ds_read_b64_tr_b16 v[156:157], v121 offset:0x1200
	ds_read_b64_tr_b16 v[158:159], v121 offset:0x1a00
	ds_read_b64_tr_b16 v[162:163], v121 offset:0x400
	ds_read_b64_tr_b16 v[164:165], v121 offset:0xc00
	ds_read_b64_tr_b16 v[166:167], v121 offset:0x1400
	ds_read_b64_tr_b16 v[168:169], v121 offset:0x1c00
	ds_read_b64_tr_b16 v[170:171], v121 offset:0x600
	ds_read_b64_tr_b16 v[172:173], v121 offset:0xe00
	ds_read_b64_tr_b16 v[174:175], v121 offset:0x1600
	ds_read_b64_tr_b16 v[176:177], v121 offset:0x1e00
	s_setprio 2
	v_exp_f32_e32 v64, v64
	v_exp_f32_e32 v65, v65
	v_exp_f32_e32 v66, v66
	v_exp_f32_e32 v67, v67
	v_exp_f32_e32 v68, v68
	v_exp_f32_e32 v69, v69
	v_add_f32_e32 v126, v65, v64
	v_exp_f32_e32 v70, v70
	v_add_f32_e32 v126, v66, v126
	v_exp_f32_e32 v71, v71
	v_add_f32_e32 v126, v67, v126
	v_exp_f32_e32 v72, v72
	v_add_f32_e32 v126, v68, v126
	v_exp_f32_e32 v73, v73
	v_add_f32_e32 v126, v69, v126
	v_exp_f32_e32 v74, v74
	v_add_f32_e32 v126, v70, v126
	v_exp_f32_e32 v75, v75
	v_add_f32_e32 v126, v71, v126
	v_exp_f32_e32 v76, v76
	v_add_f32_e32 v126, v72, v126
	v_exp_f32_e32 v77, v77
	v_add_f32_e32 v126, v73, v126
	v_exp_f32_e32 v78, v78
	v_add_f32_e32 v126, v74, v126
	v_exp_f32_e32 v79, v79
	v_add_f32_e32 v126, v75, v126
	v_add_f32_e32 v126, v76, v126
	v_add_f32_e32 v126, v77, v126
	v_add_f32_e32 v126, v78, v126
	v_add_f32_e32 v126, v79, v126
	v_add_f32_e32 v120, v126, v120
	v_cvt_pk_bf16_f32 v64, v64, v65
	v_cvt_pk_bf16_f32 v65, v66, v67
	v_cvt_pk_bf16_f32 v66, v68, v69
	v_cvt_pk_bf16_f32 v67, v70, v71
	v_cvt_pk_bf16_f32 v68, v72, v73
	v_cvt_pk_bf16_f32 v69, v74, v75
	v_cvt_pk_bf16_f32 v70, v76, v77
	v_cvt_pk_bf16_f32 v71, v78, v79
	s_waitcnt lgkmcnt(0)
	s_setprio 3
	v_mfma_f32_32x32x16_bf16 v[0:15], v[64:67], v[144:147], v[0:15]
	s_add_i32 s74, s22, 0xffffc000
	s_and_b32 s74, s74, 0x6000
	s_sub_i32 s3, s0, s98
	s_cmp_lt_u32 s3, s100
	v_mfma_f32_32x32x16_bf16 v[48:63], v[64:67], v[152:155], v[48:63]
	v_mfma_f32_32x32x16_bf16 v[32:47], v[64:67], v[162:165], v[32:47]
	v_mfma_f32_32x32x16_bf16 v[16:31], v[64:67], v[170:173], v[16:31]
	v_mfma_f32_32x32x16_bf16 v[0:15], v[68:71], v[148:151], v[0:15]
	v_mfma_f32_32x32x16_bf16 v[48:63], v[68:71], v[156:159], v[48:63]
	v_mfma_f32_32x32x16_bf16 v[32:47], v[68:71], v[166:169], v[32:47]
	v_mfma_f32_32x32x16_bf16 v[16:31], v[68:71], v[174:177], v[16:31]
	v_add_u32_e32 v196, s74, v107
	v_mfma_f32_32x32x16_bf16 v[64:79], v[122:125], v[92:95], 0
	v_add_u32_e32 v197, s74, v108
	v_mfma_f32_32x32x16_bf16 v[64:79], v[132:135], v[88:91], v[64:79]
	v_add_u32_e32 v198, s74, v109
	v_mfma_f32_32x32x16_bf16 v[64:79], v[136:139], v[84:87], v[64:79]
	v_add_u32_e32 v199, s74, v110
	v_mfma_f32_32x32x16_bf16 v[64:79], v[140:143], v[80:83], v[64:79]
	s_setprio 0
	s_cbranch_scc1 .Lhw_d0_b_dtd0bias1
.Lhw_d0_b_n1924:
	ds_read_b128 v[124:127], v196
	ds_read_b128 v[132:135], v197
	ds_read_b128 v[136:139], v198
	ds_read_b128 v[140:143], v199
	ds_read_b64_tr_b16 v[144:145], v121 offset:0x2000
	ds_read_b64_tr_b16 v[146:147], v121 offset:0x2800
	ds_read_b64_tr_b16 v[148:149], v121 offset:0x3000
	ds_read_b64_tr_b16 v[150:151], v121 offset:0x3800
	ds_read_b64_tr_b16 v[152:153], v121 offset:0x2200
	ds_read_b64_tr_b16 v[154:155], v121 offset:0x2a00
	ds_read_b64_tr_b16 v[156:157], v121 offset:0x3200
	ds_read_b64_tr_b16 v[158:159], v121 offset:0x3a00
	ds_read_b64_tr_b16 v[162:163], v121 offset:0x2400
	ds_read_b64_tr_b16 v[164:165], v121 offset:0x2c00
	ds_read_b64_tr_b16 v[166:167], v121 offset:0x3400
	ds_read_b64_tr_b16 v[168:169], v121 offset:0x3c00
	ds_read_b64_tr_b16 v[170:171], v121 offset:0x2600
	ds_read_b64_tr_b16 v[172:173], v121 offset:0x2e00
	ds_read_b64_tr_b16 v[174:175], v121 offset:0x3600
	ds_read_b64_tr_b16 v[176:177], v121 offset:0x3e00
	s_setprio 2
	v_exp_f32_e32 v64, v64
	v_exp_f32_e32 v65, v65
	v_exp_f32_e32 v66, v66
	v_exp_f32_e32 v67, v67
	v_exp_f32_e32 v68, v68
	v_exp_f32_e32 v69, v69
	v_add_f32_e32 v121, v65, v64
	v_exp_f32_e32 v70, v70
	v_add_f32_e32 v121, v66, v121
	v_exp_f32_e32 v71, v71
	v_add_f32_e32 v121, v67, v121
	v_exp_f32_e32 v72, v72
	v_add_f32_e32 v121, v68, v121
	v_exp_f32_e32 v73, v73
	v_add_f32_e32 v121, v69, v121
	v_exp_f32_e32 v74, v74
	v_add_f32_e32 v121, v70, v121
	v_exp_f32_e32 v75, v75
	v_add_f32_e32 v121, v71, v121
	v_exp_f32_e32 v76, v76
	v_add_f32_e32 v121, v72, v121
	v_exp_f32_e32 v77, v77
	v_add_f32_e32 v121, v73, v121
	v_exp_f32_e32 v78, v78
	v_add_f32_e32 v121, v74, v121
	v_exp_f32_e32 v79, v79
	v_add_f32_e32 v121, v75, v121
	v_add_f32_e32 v121, v76, v121
	v_add_f32_e32 v121, v77, v121
	v_add_f32_e32 v121, v78, v121
	v_add_f32_e32 v121, v79, v121
	v_add_f32_e32 v120, v120, v121
	v_cvt_pk_bf16_f32 v64, v64, v65
	v_cvt_pk_bf16_f32 v65, v66, v67
	v_cvt_pk_bf16_f32 v66, v68, v69
	v_cvt_pk_bf16_f32 v67, v70, v71
	v_cvt_pk_bf16_f32 v68, v72, v73
	v_cvt_pk_bf16_f32 v69, v74, v75
	v_cvt_pk_bf16_f32 v70, v76, v77
	v_cvt_pk_bf16_f32 v71, v78, v79
	s_waitcnt lgkmcnt(0)
	s_setprio 3
	s_waitcnt vmcnt(3)
	s_barrier
	v_mfma_f32_32x32x16_bf16 v[0:15], v[64:67], v[144:147], v[0:15]
	s_sub_i32 s74, s0, s55
	s_cmp_lt_u32 s74, s100
	v_mfma_f32_32x32x16_bf16 v[48:63], v[64:67], v[152:155], v[48:63]
	v_mfma_f32_32x32x16_bf16 v[32:47], v[64:67], v[162:165], v[32:47]
	v_mfma_f32_32x32x16_bf16 v[16:31], v[64:67], v[170:173], v[16:31]
	v_mfma_f32_32x32x16_bf16 v[0:15], v[68:71], v[148:151], v[0:15]
	v_mfma_f32_32x32x16_bf16 v[48:63], v[68:71], v[156:159], v[48:63]
	v_mfma_f32_32x32x16_bf16 v[32:47], v[68:71], v[166:169], v[32:47]
	v_mfma_f32_32x32x16_bf16 v[16:31], v[68:71], v[174:177], v[16:31]
	v_lshl_add_u32 v121, s64, 14, v106
	v_mfma_f32_32x32x16_bf16 v[64:79], v[124:127], v[92:95], 0
	v_add_u32_e32 v100, s8, v100
	v_mfma_f32_32x32x16_bf16 v[64:79], v[132:135], v[88:91], v[64:79]
	v_add_u32_e32 v102, s8, v102
	v_mfma_f32_32x32x16_bf16 v[64:79], v[136:139], v[84:87], v[64:79]
	v_add_u32_e32 v104, s8, v104
	v_mfma_f32_32x32x16_bf16 v[64:79], v[140:143], v[80:83], v[64:79]
	s_cbranch_scc1 .Lhw_d0_b_dtd0bias2

; DI void expsum(f32x16& p, float& l_reg, bf16x8& pa0, bf16x8& pa1) {
; #pragma unroll
;     for (int r = 0; r < 16; ++r) p[r] = __builtin_amdgcn_exp2f(p[r]);
;     float ps = 0.f;
; #pragma unroll
;     for (int r = 0; r < 16; ++r) ps += p[r];
;     l_reg += ps; asm volatile("" : "+v"(l_reg));
;     ...
;     ATT_PK4(p, 0, pa0); ATT_PK4(p, 8, pa1);
;     ...
; }
; DI int v_rd_base(int lane) { return ((lane & 3) << 3) | (((lane >> 2) & 3) << 6) | (((lane >> 4) & 1) << 5) | (((lane >> 5) & 1) << 8); }
; template <int OFF> DI s16x4 tr_read(int vb) { s16x4 r; asm volatile("ds_read_b64_tr_b16 %0, %1 offset:%2" : "=&v"(r) : "v"(vb), "i"(OFF) : "memory"); return r; }
; template <int H> DI void v_reads(s16x4* vf, int vb) {
;     vf[0] = tr_read<v_rd_off(0, 2 * H, 0)>(vb); vf[1] = tr_read<v_rd_off(0, 2 * H, 1)>(vb); vf[2] = tr_read<v_rd_off(0, 2 * H + 1, 0)>(vb); vf[3] = tr_read<v_rd_off(0, 2 * H + 1, 1)>(vb);
;     vf[4] = tr_read<v_rd_off(1, 2 * H, 0)>(vb); vf[5] = tr_read<v_rd_off(1, 2 * H, 1)>(vb); vf[6] = tr_read<v_rd_off(1, 2 * H + 1, 0)>(vb); vf[7] = tr_read<v_rd_off(1, 2 * H + 1, 1)>(vb);
;     vf[8] = tr_read<v_rd_off(2, 2 * H, 0)>(vb); vf[9] = tr_read<v_rd_off(2, 2 * H, 1)>(vb); vf[10] = tr_read<v_rd_off(2, 2 * H + 1, 0)>(vb); vf[11] = tr_read<v_rd_off(2, 2 * H + 1, 1)>(vb);
;     vf[12] = tr_read<v_rd_off(3, 2 * H, 0)>(vb); vf[13] = tr_read<v_rd_off(3, 2 * H, 1)>(vb); vf[14] = tr_read<v_rd_off(3, 2 * H + 1, 0)>(vb); vf[15] = tr_read<v_rd_off(3, 2 * H + 1, 1)>(vb);
; }
; DI void pv_mma(f32x16* o, const s16x4* vf, bf16x8 pa0, bf16x8 pa1) {
;     ...
; #pragma unroll
;     for (int d0 = 0; d0 < 4; ++d0) {
;         o[d0] = __builtin_amdgcn_mfma_f32_32x32x16_bf16(pa0, ATT_PK(vf[4 * d0], vf[4 * d0 + 1]), o[d0], 0, 0, 0);
;         o[d0] = __builtin_amdgcn_mfma_f32_32x32x16_bf16(pa1, ATT_PK(vf[4 * d0 + 2], vf[4 * d0 + 3]), o[d0], 0, 0, 0); }
;     ...
; }
.LBB0_1922:
	ds_read_b128 v[122:125], v196 offset:4096
	ds_read_b128 v[132:135], v197 offset:4096
	s_lshl_b32 s2, s1, 14
	ds_read_b128 v[136:139], v198 offset:4096
	ds_read_b128 v[140:143], v199 offset:4096
	ds_read_b64_tr_b16 v[144:145], v121 offset:0
	ds_read_b64_tr_b16 v[146:147], v121 offset:0x800
	ds_read_b64_tr_b16 v[148:149], v121 offset:0x1000
	ds_read_b64_tr_b16 v[150:151], v121 offset:0x1800
	ds_read_b64_tr_b16 v[152:153], v121 offset:0x200
	ds_read_b64_tr_b16 v[154:155], v121 offset:0xa00
	ds_read_b64_tr_b16 v[156:157], v121 offset:0x1200
	ds_read_b64_tr_b16 v[158:159], v121 offset:0x1a00
	ds_read_b64_tr_b16 v[162:163], v121 offset:0x400
	ds_read_b64_tr_b16 v[164:165], v121 offset:0xc00
	ds_read_b64_tr_b16 v[166:167], v121 offset:0x1400
	ds_read_b64_tr_b16 v[168:169], v121 offset:0x1c00
	ds_read_b64_tr_b16 v[170:171], v121 offset:0x600
	ds_read_b64_tr_b16 v[172:173], v121 offset:0xe00
	ds_read_b64_tr_b16 v[174:175], v121 offset:0x1600
	ds_read_b64_tr_b16 v[176:177], v121 offset:0x1e00
	s_setprio 1
	v_exp_f32_e32 v64, v64
	v_exp_f32_e32 v65, v65
	v_exp_f32_e32 v66, v66
	v_exp_f32_e32 v67, v67
	v_exp_f32_e32 v68, v68
	v_exp_f32_e32 v69, v69
	v_add_f32_e32 v126, v65, v64
	v_exp_f32_e32 v70, v70
	v_add_f32_e32 v126, v66, v126
	v_exp_f32_e32 v71, v71
	v_add_f32_e32 v126, v67, v126
	v_exp_f32_e32 v72, v72
	v_add_f32_e32 v126, v68, v126
	v_exp_f32_e32 v73, v73
	v_add_f32_e32 v126, v69, v126
	v_exp_f32_e32 v74, v74
	v_add_f32_e32 v126, v70, v126
	v_exp_f32_e32 v75, v75
	v_add_f32_e32 v126, v71, v126
	v_exp_f32_e32 v76, v76
	v_add_f32_e32 v126, v72, v126
	v_exp_f32_e32 v77, v77
	v_add_f32_e32 v126, v73, v126
	v_exp_f32_e32 v78, v78
	v_add_f32_e32 v126, v74, v126
	v_exp_f32_e32 v79, v79
	v_add_f32_e32 v126, v75, v126
	v_add_f32_e32 v126, v76, v126
	v_add_f32_e32 v126, v77, v126
	v_add_f32_e32 v126, v78, v126
	v_add_f32_e32 v126, v79, v126
	v_add_f32_e32 v120, v126, v120
	v_cvt_pk_bf16_f32 v64, v64, v65
	v_cvt_pk_bf16_f32 v65, v66, v67
	v_cvt_pk_bf16_f32 v66, v68, v69
	v_cvt_pk_bf16_f32 v67, v70, v71
	v_cvt_pk_bf16_f32 v68, v72, v73
	v_cvt_pk_bf16_f32 v69, v74, v75
	v_cvt_pk_bf16_f32 v70, v76, v77
	v_cvt_pk_bf16_f32 v71, v78, v79
	s_waitcnt lgkmcnt(0)
	s_setprio 3
	v_mfma_f32_32x32x16_bf16 v[0:15], v[64:67], v[144:147], v[0:15]
	s_add_i32 s74, s22, 0xffffc000
	s_and_b32 s74, s74, 0x6000
	s_sub_i32 s3, s0, s98
	s_cmp_lt_u32 s3, s100
	v_mfma_f32_32x32x16_bf16 v[48:63], v[64:67], v[152:155], v[48:63]
	v_mfma_f32_32x32x16_bf16 v[32:47], v[64:67], v[162:165], v[32:47]
	v_mfma_f32_32x32x16_bf16 v[16:31], v[64:67], v[170:173], v[16:31]
	v_mfma_f32_32x32x16_bf16 v[0:15], v[68:71], v[148:151], v[0:15]
	v_mfma_f32_32x32x16_bf16 v[48:63], v[68:71], v[156:159], v[48:63]
	v_mfma_f32_32x32x16_bf16 v[32:47], v[68:71], v[166:169], v[32:47]
	v_mfma_f32_32x32x16_bf16 v[16:31], v[68:71], v[174:177], v[16:31]
	v_add_u32_e32 v196, s74, v107
	v_mfma_f32_32x32x16_bf16 v[64:79], v[122:125], v[92:95], 0
	v_add_u32_e32 v197, s74, v108
	v_mfma_f32_32x32x16_bf16 v[64:79], v[132:135], v[88:91], v[64:79]
	v_add_u32_e32 v198, s74, v109
	v_mfma_f32_32x32x16_bf16 v[64:79], v[136:139], v[84:87], v[64:79]
	v_add_u32_e32 v199, s74, v110
	v_mfma_f32_32x32x16_bf16 v[64:79], v[140:143], v[80:83], v[64:79]
	s_setprio 0
	s_cbranch_scc1 .Ldt_d0_bias1
.LBB0_1924:
	ds_read_b128 v[124:127], v196
	ds_read_b128 v[132:135], v197
	ds_read_b128 v[136:139], v198
	ds_read_b128 v[140:143], v199
	ds_read_b64_tr_b16 v[144:145], v121 offset:0x2000
	ds_read_b64_tr_b16 v[146:147], v121 offset:0x2800
	ds_read_b64_tr_b16 v[148:149], v121 offset:0x3000
	ds_read_b64_tr_b16 v[150:151], v121 offset:0x3800
	ds_read_b64_tr_b16 v[152:153], v121 offset:0x2200
	ds_read_b64_tr_b16 v[154:155], v121 offset:0x2a00
	ds_read_b64_tr_b16 v[156:157], v121 offset:0x3200
	ds_read_b64_tr_b16 v[158:159], v121 offset:0x3a00
	ds_read_b64_tr_b16 v[162:163], v121 offset:0x2400
	ds_read_b64_tr_b16 v[164:165], v121 offset:0x2c00
	ds_read_b64_tr_b16 v[166:167], v121 offset:0x3400
	ds_read_b64_tr_b16 v[168:169], v121 offset:0x3c00
	ds_read_b64_tr_b16 v[170:171], v121 offset:0x2600
	ds_read_b64_tr_b16 v[172:173], v121 offset:0x2e00
	ds_read_b64_tr_b16 v[174:175], v121 offset:0x3600
	ds_read_b64_tr_b16 v[176:177], v121 offset:0x3e00
	s_setprio 1
	v_exp_f32_e32 v64, v64
	v_exp_f32_e32 v65, v65
	v_exp_f32_e32 v66, v66
	v_exp_f32_e32 v67, v67
	v_exp_f32_e32 v68, v68
	v_exp_f32_e32 v69, v69
	v_add_f32_e32 v121, v65, v64
	v_exp_f32_e32 v70, v70
	v_add_f32_e32 v121, v66, v121
	v_exp_f32_e32 v71, v71
	v_add_f32_e32 v121, v67, v121
	v_exp_f32_e32 v72, v72
	v_add_f32_e32 v121, v68, v121
	v_exp_f32_e32 v73, v73
	v_add_f32_e32 v121, v69, v121
	v_exp_f32_e32 v74, v74
	v_add_f32_e32 v121, v70, v121
	v_exp_f32_e32 v75, v75
	v_add_f32_e32 v121, v71, v121
	v_exp_f32_e32 v76, v76
	v_add_f32_e32 v121, v72, v121
	v_exp_f32_e32 v77, v77
	v_add_f32_e32 v121, v73, v121
	v_exp_f32_e32 v78, v78
	v_add_f32_e32 v121, v74, v121
	v_exp_f32_e32 v79, v79
	v_add_f32_e32 v121, v75, v121
	v_add_f32_e32 v121, v76, v121
	v_add_f32_e32 v121, v77, v121
	v_add_f32_e32 v121, v78, v121
	v_add_f32_e32 v121, v79, v121
	v_add_f32_e32 v120, v120, v121
	v_cvt_pk_bf16_f32 v64, v64, v65
	v_cvt_pk_bf16_f32 v65, v66, v67
	v_cvt_pk_bf16_f32 v66, v68, v69
	v_cvt_pk_bf16_f32 v67, v70, v71
	v_cvt_pk_bf16_f32 v68, v72, v73
	v_cvt_pk_bf16_f32 v69, v74, v75
	v_cvt_pk_bf16_f32 v70, v76, v77
	v_cvt_pk_bf16_f32 v71, v78, v79
	s_waitcnt lgkmcnt(0)
	s_setprio 3
	v_mfma_f32_32x32x16_bf16 v[0:15], v[64:67], v[144:147], v[0:15]
	s_sub_i32 s74, s0, s55
	s_cmp_lt_u32 s74, s100
	v_mfma_f32_32x32x16_bf16 v[48:63], v[64:67], v[152:155], v[48:63]
	v_mfma_f32_32x32x16_bf16 v[32:47], v[64:67], v[162:165], v[32:47]
	v_mfma_f32_32x32x16_bf16 v[16:31], v[64:67], v[170:173], v[16:31]
	v_mfma_f32_32x32x16_bf16 v[0:15], v[68:71], v[148:151], v[0:15]
	v_mfma_f32_32x32x16_bf16 v[48:63], v[68:71], v[156:159], v[48:63]
	v_mfma_f32_32x32x16_bf16 v[32:47], v[68:71], v[166:169], v[32:47]
	v_mfma_f32_32x32x16_bf16 v[16:31], v[68:71], v[174:177], v[16:31]
	v_lshl_add_u32 v121, s64, 14, v106
	v_mfma_f32_32x32x16_bf16 v[64:79], v[124:127], v[92:95], 0
	v_add_u32_e32 v100, s8, v100
	v_mfma_f32_32x32x16_bf16 v[64:79], v[132:135], v[88:91], v[64:79]
	v_add_u32_e32 v102, s8, v102
	v_mfma_f32_32x32x16_bf16 v[64:79], v[136:139], v[84:87], v[64:79]
	v_add_u32_e32 v104, s8, v104
	v_mfma_f32_32x32x16_bf16 v[64:79], v[140:143], v[80:83], v[64:79]
	s_cbranch_scc1 .Ldt_d0_bias2

; DI void expsum(f32x16& p, float& l_reg, bf16x8& pa0, bf16x8& pa1) {
; #pragma unroll
;     for (int r = 0; r < 16; ++r) p[r] = __builtin_amdgcn_exp2f(p[r]);
;     float ps = 0.f;
; #pragma unroll
;     for (int r = 0; r < 16; ++r) ps += p[r];
;     l_reg += ps; asm volatile("" : "+v"(l_reg));
;     ...
;     ATT_PK4(p, 0, pa0); ATT_PK4(p, 8, pa1);
;     ...
; }
; DI int v_rd_base(int lane) { return ((lane & 3) << 3) | (((lane >> 2) & 3) << 6) | (((lane >> 4) & 1) << 5) | (((lane >> 5) & 1) << 8); }
; template <int OFF> DI s16x4 tr_read(int vb) { s16x4 r; asm volatile("ds_read_b64_tr_b16 %0, %1 offset:%2" : "=&v"(r) : "v"(vb), "i"(OFF) : "memory"); return r; }
; template <int H> DI void v_reads(s16x4* vf, int vb) {
;     vf[0] = tr_read<v_rd_off(0, 2 * H, 0)>(vb); vf[1] = tr_read<v_rd_off(0, 2 * H, 1)>(vb); vf[2] = tr_read<v_rd_off(0, 2 * H + 1, 0)>(vb); vf[3] = tr_read<v_rd_off(0, 2 * H + 1, 1)>(vb);
;     vf[4] = tr_read<v_rd_off(1, 2 * H, 0)>(vb); vf[5] = tr_read<v_rd_off(1, 2 * H, 1)>(vb); vf[6] = tr_read<v_rd_off(1, 2 * H + 1, 0)>(vb); vf[7] = tr_read<v_rd_off(1, 2 * H + 1, 1)>(vb);
;     vf[8] = tr_read<v_rd_off(2, 2 * H, 0)>(vb); vf[9] = tr_read<v_rd_off(2, 2 * H, 1)>(vb); vf[10] = tr_read<v_rd_off(2, 2 * H + 1, 0)>(vb); vf[11] = tr_read<v_rd_off(2, 2 * H + 1, 1)>(vb);
;     vf[12] = tr_read<v_rd_off(3, 2 * H, 0)>(vb); vf[13] = tr_read<v_rd_off(3, 2 * H, 1)>(vb); vf[14] = tr_read<v_rd_off(3, 2 * H + 1, 0)>(vb); vf[15] = tr_read<v_rd_off(3, 2 * H + 1, 1)>(vb);
; }
; DI void pv_mma(f32x16* o, const s16x4* vf, bf16x8 pa0, bf16x8 pa1) {
;     ...
; #pragma unroll
;     for (int d0 = 0; d0 < 4; ++d0) {
;         o[d0] = __builtin_amdgcn_mfma_f32_32x32x16_bf16(pa0, ATT_PK(vf[4 * d0], vf[4 * d0 + 1]), o[d0], 0, 0, 0);
;         o[d0] = __builtin_amdgcn_mfma_f32_32x32x16_bf16(pa1, ATT_PK(vf[4 * d0 + 2], vf[4 * d0 + 3]), o[d0], 0, 0, 0); }
;     ...
; }
.Lhw_d1_b_n1953:
	ds_read_b128 v[122:125], v196 offset:4096
	ds_read_b128 v[132:135], v197 offset:4096
	s_lshl_b32 s2, s23, 14
	ds_read_b128 v[136:139], v198 offset:4096
	ds_read_b128 v[140:143], v199 offset:4096
	ds_read_b64_tr_b16 v[144:145], v121 offset:0
	ds_read_b64_tr_b16 v[146:147], v121 offset:0x800
	ds_read_b64_tr_b16 v[148:149], v121 offset:0x1000
	ds_read_b64_tr_b16 v[150:151], v121 offset:0x1800
	ds_read_b64_tr_b16 v[152:153], v121 offset:0x200
	ds_read_b64_tr_b16 v[154:155], v121 offset:0xa00
	ds_read_b64_tr_b16 v[156:157], v121 offset:0x1200
	ds_read_b64_tr_b16 v[158:159], v121 offset:0x1a00
	ds_read_b64_tr_b16 v[162:163], v121 offset:0x400
	ds_read_b64_tr_b16 v[164:165], v121 offset:0xc00
	ds_read_b64_tr_b16 v[166:167], v121 offset:0x1400
	ds_read_b64_tr_b16 v[168:169], v121 offset:0x1c00
	ds_read_b64_tr_b16 v[170:171], v121 offset:0x600
	ds_read_b64_tr_b16 v[172:173], v121 offset:0xe00
	ds_read_b64_tr_b16 v[174:175], v121 offset:0x1600
	ds_read_b64_tr_b16 v[176:177], v121 offset:0x1e00
	s_setprio 2
	v_exp_f32_e32 v64, v64
	v_exp_f32_e32 v65, v65
	v_exp_f32_e32 v66, v66
	v_exp_f32_e32 v67, v67
	v_exp_f32_e32 v68, v68
	v_exp_f32_e32 v69, v69
	v_add_f32_e32 v126, v65, v64
	v_exp_f32_e32 v70, v70
	v_add_f32_e32 v126, v66, v126
	v_exp_f32_e32 v71, v71
	v_add_f32_e32 v126, v67, v126
	v_exp_f32_e32 v72, v72
	v_add_f32_e32 v126, v68, v126
	v_exp_f32_e32 v73, v73
	v_add_f32_e32 v126, v69, v126
	v_exp_f32_e32 v74, v74
	v_add_f32_e32 v126, v70, v126
	v_exp_f32_e32 v75, v75
	v_add_f32_e32 v126, v71, v126
	v_exp_f32_e32 v76, v76
	v_add_f32_e32 v126, v72, v126
	v_exp_f32_e32 v77, v77
	v_add_f32_e32 v126, v73, v126
	v_exp_f32_e32 v78, v78
	v_add_f32_e32 v126, v74, v126
	v_exp_f32_e32 v79, v79
	v_add_f32_e32 v126, v75, v126
	v_add_f32_e32 v126, v76, v126
	v_add_f32_e32 v126, v77, v126
	v_add_f32_e32 v126, v78, v126
	v_add_f32_e32 v126, v79, v126
	v_add_f32_e32 v120, v126, v120
	v_cvt_pk_bf16_f32 v64, v64, v65
	v_cvt_pk_bf16_f32 v65, v66, v67
	v_cvt_pk_bf16_f32 v66, v68, v69
	v_cvt_pk_bf16_f32 v67, v70, v71
	v_cvt_pk_bf16_f32 v68, v72, v73
	v_cvt_pk_bf16_f32 v69, v74, v75
	v_cvt_pk_bf16_f32 v70, v76, v77
	v_cvt_pk_bf16_f32 v71, v78, v79
	s_waitcnt lgkmcnt(0)
	s_setprio 3
	v_mfma_f32_32x32x16_bf16 v[0:15], v[64:67], v[144:147], v[0:15]
	s_add_i32 s74, s22, 0xffffc000
	s_and_b32 s74, s74, 0x6000
	s_sub_i32 s3, s0, s98
	s_cmp_lt_u32 s3, s100
	v_mfma_f32_32x32x16_bf16 v[48:63], v[64:67], v[152:155], v[48:63]
	v_mfma_f32_32x32x16_bf16 v[16:31], v[64:67], v[162:165], v[16:31]
	v_mfma_f32_32x32x16_bf16 v[32:47], v[64:67], v[170:173], v[32:47]
	v_mfma_f32_32x32x16_bf16 v[0:15], v[68:71], v[148:151], v[0:15]
	v_mfma_f32_32x32x16_bf16 v[48:63], v[68:71], v[156:159], v[48:63]
	v_mfma_f32_32x32x16_bf16 v[16:31], v[68:71], v[166:169], v[16:31]
	v_mfma_f32_32x32x16_bf16 v[32:47], v[68:71], v[174:177], v[32:47]
	v_add_u32_e32 v196, s74, v107
	v_mfma_f32_32x32x16_bf16 v[64:79], v[122:125], v[92:95], 0
	v_add_u32_e32 v197, s74, v108
	v_mfma_f32_32x32x16_bf16 v[64:79], v[132:135], v[88:91], v[64:79]
	v_add_u32_e32 v198, s74, v109
	v_mfma_f32_32x32x16_bf16 v[64:79], v[136:139], v[84:87], v[64:79]
	v_add_u32_e32 v199, s74, v110
	v_mfma_f32_32x32x16_bf16 v[64:79], v[140:143], v[80:83], v[64:79]
	s_setprio 0
	s_cbranch_scc1 .Lhw_d1_b_dtd1bias1
.Lhw_d1_b_n1955:
	ds_read_b128 v[124:127], v196
	ds_read_b128 v[132:135], v197
	ds_read_b128 v[136:139], v198
	ds_read_b128 v[140:143], v199
	ds_read_b64_tr_b16 v[144:145], v121 offset:0x2000
	ds_read_b64_tr_b16 v[146:147], v121 offset:0x2800
	ds_read_b64_tr_b16 v[148:149], v121 offset:0x3000
	ds_read_b64_tr_b16 v[150:151], v121 offset:0x3800
	ds_read_b64_tr_b16 v[152:153], v121 offset:0x2200
	ds_read_b64_tr_b16 v[154:155], v121 offset:0x2a00
	ds_read_b64_tr_b16 v[156:157], v121 offset:0x3200
	ds_read_b64_tr_b16 v[158:159], v121 offset:0x3a00
	ds_read_b64_tr_b16 v[162:163], v121 offset:0x2400
	ds_read_b64_tr_b16 v[164:165], v121 offset:0x2c00
	ds_read_b64_tr_b16 v[166:167], v121 offset:0x3400
	ds_read_b64_tr_b16 v[168:169], v121 offset:0x3c00
	ds_read_b64_tr_b16 v[170:171], v121 offset:0x2600
	ds_read_b64_tr_b16 v[172:173], v121 offset:0x2e00
	ds_read_b64_tr_b16 v[174:175], v121 offset:0x3600
	ds_read_b64_tr_b16 v[176:177], v121 offset:0x3e00
	s_setprio 2
	v_exp_f32_e32 v64, v64
	v_exp_f32_e32 v65, v65
	v_exp_f32_e32 v66, v66
	v_exp_f32_e32 v67, v67
	v_exp_f32_e32 v68, v68
	v_exp_f32_e32 v69, v69
	v_add_f32_e32 v121, v65, v64
	v_exp_f32_e32 v70, v70
	v_add_f32_e32 v121, v66, v121
	v_exp_f32_e32 v71, v71
	v_add_f32_e32 v121, v67, v121
	v_exp_f32_e32 v72, v72
	v_add_f32_e32 v121, v68, v121
	v_exp_f32_e32 v73, v73
	v_add_f32_e32 v121, v69, v121
	v_exp_f32_e32 v74, v74
	v_add_f32_e32 v121, v70, v121
	v_exp_f32_e32 v75, v75
	v_add_f32_e32 v121, v71, v121
	v_exp_f32_e32 v76, v76
	v_add_f32_e32 v121, v72, v121
	v_exp_f32_e32 v77, v77
	v_add_f32_e32 v121, v73, v121
	v_exp_f32_e32 v78, v78
	v_add_f32_e32 v121, v74, v121
	v_exp_f32_e32 v79, v79
	v_add_f32_e32 v121, v75, v121
	v_add_f32_e32 v121, v76, v121
	v_add_f32_e32 v121, v77, v121
	v_add_f32_e32 v121, v78, v121
	v_add_f32_e32 v121, v79, v121
	v_add_f32_e32 v120, v120, v121
	v_cvt_pk_bf16_f32 v64, v64, v65
	v_cvt_pk_bf16_f32 v65, v66, v67
	v_cvt_pk_bf16_f32 v66, v68, v69
	v_cvt_pk_bf16_f32 v67, v70, v71
	v_cvt_pk_bf16_f32 v68, v72, v73
	v_cvt_pk_bf16_f32 v69, v74, v75
	v_cvt_pk_bf16_f32 v70, v76, v77
	v_cvt_pk_bf16_f32 v71, v78, v79
	s_waitcnt lgkmcnt(0)
	s_setprio 3
	s_waitcnt vmcnt(3)
	s_barrier
	v_mfma_f32_32x32x16_bf16 v[0:15], v[64:67], v[144:147], v[0:15]
	s_sub_i32 s74, s0, s47
	s_cmp_lt_u32 s74, s100
	v_mfma_f32_32x32x16_bf16 v[48:63], v[64:67], v[152:155], v[48:63]
	v_mfma_f32_32x32x16_bf16 v[16:31], v[64:67], v[162:165], v[16:31]
	v_mfma_f32_32x32x16_bf16 v[32:47], v[64:67], v[170:173], v[32:47]
	v_mfma_f32_32x32x16_bf16 v[0:15], v[68:71], v[148:151], v[0:15]
	v_mfma_f32_32x32x16_bf16 v[48:63], v[68:71], v[156:159], v[48:63]
	v_mfma_f32_32x32x16_bf16 v[16:31], v[68:71], v[166:169], v[16:31]
	v_mfma_f32_32x32x16_bf16 v[32:47], v[68:71], v[174:177], v[32:47]
	v_lshl_add_u32 v121, s49, 14, v106
	v_mfma_f32_32x32x16_bf16 v[64:79], v[124:127], v[92:95], 0
	v_add_u32_e32 v100, s8, v100
	v_mfma_f32_32x32x16_bf16 v[64:79], v[132:135], v[88:91], v[64:79]
	v_add_u32_e32 v102, s8, v102
	v_mfma_f32_32x32x16_bf16 v[64:79], v[136:139], v[84:87], v[64:79]
	v_add_u32_e32 v104, s8, v104
	v_mfma_f32_32x32x16_bf16 v[64:79], v[140:143], v[80:83], v[64:79]
	s_cbranch_scc1 .Lhw_d1_b_dtd1bias2

; DI void expsum(f32x16& p, float& l_reg, bf16x8& pa0, bf16x8& pa1) {
; #pragma unroll
;     for (int r = 0; r < 16; ++r) p[r] = __builtin_amdgcn_exp2f(p[r]);
;     float ps = 0.f;
; #pragma unroll
;     for (int r = 0; r < 16; ++r) ps += p[r];
;     l_reg += ps; asm volatile("" : "+v"(l_reg));
;     ...
;     ATT_PK4(p, 0, pa0); ATT_PK4(p, 8, pa1);
;     ...
; }
; DI int v_rd_base(int lane) { return ((lane & 3) << 3) | (((lane >> 2) & 3) << 6) | (((lane >> 4) & 1) << 5) | (((lane >> 5) & 1) << 8); }
; template <int OFF> DI s16x4 tr_read(int vb) { s16x4 r; asm volatile("ds_read_b64_tr_b16 %0, %1 offset:%2" : "=&v"(r) : "v"(vb), "i"(OFF) : "memory"); return r; }
; template <int H> DI void v_reads(s16x4* vf, int vb) {
;     vf[0] = tr_read<v_rd_off(0, 2 * H, 0)>(vb); vf[1] = tr_read<v_rd_off(0, 2 * H, 1)>(vb); vf[2] = tr_read<v_rd_off(0, 2 * H + 1, 0)>(vb); vf[3] = tr_read<v_rd_off(0, 2 * H + 1, 1)>(vb);
;     vf[4] = tr_read<v_rd_off(1, 2 * H, 0)>(vb); vf[5] = tr_read<v_rd_off(1, 2 * H, 1)>(vb); vf[6] = tr_read<v_rd_off(1, 2 * H + 1, 0)>(vb); vf[7] = tr_read<v_rd_off(1, 2 * H + 1, 1)>(vb);
;     vf[8] = tr_read<v_rd_off(2, 2 * H, 0)>(vb); vf[9] = tr_read<v_rd_off(2, 2 * H, 1)>(vb); vf[10] = tr_read<v_rd_off(2, 2 * H + 1, 0)>(vb); vf[11] = tr_read<v_rd_off(2, 2 * H + 1, 1)>(vb);
;     vf[12] = tr_read<v_rd_off(3, 2 * H, 0)>(vb); vf[13] = tr_read<v_rd_off(3, 2 * H, 1)>(vb); vf[14] = tr_read<v_rd_off(3, 2 * H + 1, 0)>(vb); vf[15] = tr_read<v_rd_off(3, 2 * H + 1, 1)>(vb);
; }
; DI void pv_mma(f32x16* o, const s16x4* vf, bf16x8 pa0, bf16x8 pa1) {
;     ...
; #pragma unroll
;     for (int d0 = 0; d0 < 4; ++d0) {
;         o[d0] = __builtin_amdgcn_mfma_f32_32x32x16_bf16(pa0, ATT_PK(vf[4 * d0], vf[4 * d0 + 1]), o[d0], 0, 0, 0);
;         o[d0] = __builtin_amdgcn_mfma_f32_32x32x16_bf16(pa1, ATT_PK(vf[4 * d0 + 2], vf[4 * d0 + 3]), o[d0], 0, 0, 0); }
;     ...
; }
.LBB0_1953:
	ds_read_b128 v[122:125], v196 offset:4096
	ds_read_b128 v[132:135], v197 offset:4096
	s_lshl_b32 s2, s23, 14
	ds_read_b128 v[136:139], v198 offset:4096
	ds_read_b128 v[140:143], v199 offset:4096
	ds_read_b64_tr_b16 v[144:145], v121 offset:0
	ds_read_b64_tr_b16 v[146:147], v121 offset:0x800
	ds_read_b64_tr_b16 v[148:149], v121 offset:0x1000
	ds_read_b64_tr_b16 v[150:151], v121 offset:0x1800
	ds_read_b64_tr_b16 v[152:153], v121 offset:0x200
	ds_read_b64_tr_b16 v[154:155], v121 offset:0xa00
	ds_read_b64_tr_b16 v[156:157], v121 offset:0x1200
	ds_read_b64_tr_b16 v[158:159], v121 offset:0x1a00
	ds_read_b64_tr_b16 v[162:163], v121 offset:0x400
	ds_read_b64_tr_b16 v[164:165], v121 offset:0xc00
	ds_read_b64_tr_b16 v[166:167], v121 offset:0x1400
	ds_read_b64_tr_b16 v[168:169], v121 offset:0x1c00
	ds_read_b64_tr_b16 v[170:171], v121 offset:0x600
	ds_read_b64_tr_b16 v[172:173], v121 offset:0xe00
	ds_read_b64_tr_b16 v[174:175], v121 offset:0x1600
	ds_read_b64_tr_b16 v[176:177], v121 offset:0x1e00
	s_setprio 1
	v_exp_f32_e32 v64, v64
	v_exp_f32_e32 v65, v65
	v_exp_f32_e32 v66, v66
	v_exp_f32_e32 v67, v67
	v_exp_f32_e32 v68, v68
	v_exp_f32_e32 v69, v69
	v_add_f32_e32 v126, v65, v64
	v_exp_f32_e32 v70, v70
	v_add_f32_e32 v126, v66, v126
	v_exp_f32_e32 v71, v71
	v_add_f32_e32 v126, v67, v126
	v_exp_f32_e32 v72, v72
	v_add_f32_e32 v126, v68, v126
	v_exp_f32_e32 v73, v73
	v_add_f32_e32 v126, v69, v126
	v_exp_f32_e32 v74, v74
	v_add_f32_e32 v126, v70, v126
	v_exp_f32_e32 v75, v75
	v_add_f32_e32 v126, v71, v126
	v_exp_f32_e32 v76, v76
	v_add_f32_e32 v126, v72, v126
	v_exp_f32_e32 v77, v77
	v_add_f32_e32 v126, v73, v126
	v_exp_f32_e32 v78, v78
	v_add_f32_e32 v126, v74, v126
	v_exp_f32_e32 v79, v79
	v_add_f32_e32 v126, v75, v126
	v_add_f32_e32 v126, v76, v126
	v_add_f32_e32 v126, v77, v126
	v_add_f32_e32 v126, v78, v126
	v_add_f32_e32 v126, v79, v126
	v_add_f32_e32 v120, v126, v120
	v_cvt_pk_bf16_f32 v64, v64, v65
	v_cvt_pk_bf16_f32 v65, v66, v67
	v_cvt_pk_bf16_f32 v66, v68, v69
	v_cvt_pk_bf16_f32 v67, v70, v71
	v_cvt_pk_bf16_f32 v68, v72, v73
	v_cvt_pk_bf16_f32 v69, v74, v75
	v_cvt_pk_bf16_f32 v70, v76, v77
	v_cvt_pk_bf16_f32 v71, v78, v79
	s_waitcnt lgkmcnt(0)
	s_setprio 3
	v_mfma_f32_32x32x16_bf16 v[0:15], v[64:67], v[144:147], v[0:15]
	s_add_i32 s74, s22, 0xffffc000
	s_and_b32 s74, s74, 0x6000
	s_sub_i32 s3, s0, s98
	s_cmp_lt_u32 s3, s100
	v_mfma_f32_32x32x16_bf16 v[48:63], v[64:67], v[152:155], v[48:63]
	v_mfma_f32_32x32x16_bf16 v[16:31], v[64:67], v[162:165], v[16:31]
	v_mfma_f32_32x32x16_bf16 v[32:47], v[64:67], v[170:173], v[32:47]
	v_mfma_f32_32x32x16_bf16 v[0:15], v[68:71], v[148:151], v[0:15]
	v_mfma_f32_32x32x16_bf16 v[48:63], v[68:71], v[156:159], v[48:63]
	v_mfma_f32_32x32x16_bf16 v[16:31], v[68:71], v[166:169], v[16:31]
	v_mfma_f32_32x32x16_bf16 v[32:47], v[68:71], v[174:177], v[32:47]
	v_add_u32_e32 v196, s74, v107
	v_mfma_f32_32x32x16_bf16 v[64:79], v[122:125], v[92:95], 0
	v_add_u32_e32 v197, s74, v108
	v_mfma_f32_32x32x16_bf16 v[64:79], v[132:135], v[88:91], v[64:79]
	v_add_u32_e32 v198, s74, v109
	v_mfma_f32_32x32x16_bf16 v[64:79], v[136:139], v[84:87], v[64:79]
	v_add_u32_e32 v199, s74, v110
	v_mfma_f32_32x32x16_bf16 v[64:79], v[140:143], v[80:83], v[64:79]
	s_setprio 0
	s_cbranch_scc1 .Ldt_d1_bias1
.LBB0_1955:
	ds_read_b128 v[124:127], v196
	ds_read_b128 v[132:135], v197
	ds_read_b128 v[136:139], v198
	ds_read_b128 v[140:143], v199
	ds_read_b64_tr_b16 v[144:145], v121 offset:0x2000
	ds_read_b64_tr_b16 v[146:147], v121 offset:0x2800
	ds_read_b64_tr_b16 v[148:149], v121 offset:0x3000
	ds_read_b64_tr_b16 v[150:151], v121 offset:0x3800
	ds_read_b64_tr_b16 v[152:153], v121 offset:0x2200
	ds_read_b64_tr_b16 v[154:155], v121 offset:0x2a00
	ds_read_b64_tr_b16 v[156:157], v121 offset:0x3200
	ds_read_b64_tr_b16 v[158:159], v121 offset:0x3a00
	ds_read_b64_tr_b16 v[162:163], v121 offset:0x2400
	ds_read_b64_tr_b16 v[164:165], v121 offset:0x2c00
	ds_read_b64_tr_b16 v[166:167], v121 offset:0x3400
	ds_read_b64_tr_b16 v[168:169], v121 offset:0x3c00
	ds_read_b64_tr_b16 v[170:171], v121 offset:0x2600
	ds_read_b64_tr_b16 v[172:173], v121 offset:0x2e00
	ds_read_b64_tr_b16 v[174:175], v121 offset:0x3600
	ds_read_b64_tr_b16 v[176:177], v121 offset:0x3e00
	s_setprio 1
	v_exp_f32_e32 v64, v64
	v_exp_f32_e32 v65, v65
	v_exp_f32_e32 v66, v66
	v_exp_f32_e32 v67, v67
	v_exp_f32_e32 v68, v68
	v_exp_f32_e32 v69, v69
	v_add_f32_e32 v121, v65, v64
	v_exp_f32_e32 v70, v70
	v_add_f32_e32 v121, v66, v121
	v_exp_f32_e32 v71, v71
	v_add_f32_e32 v121, v67, v121
	v_exp_f32_e32 v72, v72
	v_add_f32_e32 v121, v68, v121
	v_exp_f32_e32 v73, v73
	v_add_f32_e32 v121, v69, v121
	v_exp_f32_e32 v74, v74
	v_add_f32_e32 v121, v70, v121
	v_exp_f32_e32 v75, v75
	v_add_f32_e32 v121, v71, v121
	v_exp_f32_e32 v76, v76
	v_add_f32_e32 v121, v72, v121
	v_exp_f32_e32 v77, v77
	v_add_f32_e32 v121, v73, v121
	v_exp_f32_e32 v78, v78
	v_add_f32_e32 v121, v74, v121
	v_exp_f32_e32 v79, v79
	v_add_f32_e32 v121, v75, v121
	v_add_f32_e32 v121, v76, v121
	v_add_f32_e32 v121, v77, v121
	v_add_f32_e32 v121, v78, v121
	v_add_f32_e32 v121, v79, v121
	v_add_f32_e32 v120, v120, v121
	v_cvt_pk_bf16_f32 v64, v64, v65
	v_cvt_pk_bf16_f32 v65, v66, v67
	v_cvt_pk_bf16_f32 v66, v68, v69
	v_cvt_pk_bf16_f32 v67, v70, v71
	v_cvt_pk_bf16_f32 v68, v72, v73
	v_cvt_pk_bf16_f32 v69, v74, v75
	v_cvt_pk_bf16_f32 v70, v76, v77
	v_cvt_pk_bf16_f32 v71, v78, v79
	s_waitcnt lgkmcnt(0)
	s_setprio 3
	v_mfma_f32_32x32x16_bf16 v[0:15], v[64:67], v[144:147], v[0:15]
	s_sub_i32 s74, s0, s47
	s_cmp_lt_u32 s74, s100
	v_mfma_f32_32x32x16_bf16 v[48:63], v[64:67], v[152:155], v[48:63]
	v_mfma_f32_32x32x16_bf16 v[16:31], v[64:67], v[162:165], v[16:31]
	v_mfma_f32_32x32x16_bf16 v[32:47], v[64:67], v[170:173], v[32:47]
	v_mfma_f32_32x32x16_bf16 v[0:15], v[68:71], v[148:151], v[0:15]
	v_mfma_f32_32x32x16_bf16 v[48:63], v[68:71], v[156:159], v[48:63]
	v_mfma_f32_32x32x16_bf16 v[16:31], v[68:71], v[166:169], v[16:31]
	v_mfma_f32_32x32x16_bf16 v[32:47], v[68:71], v[174:177], v[32:47]
	v_lshl_add_u32 v121, s49, 14, v106
	v_mfma_f32_32x32x16_bf16 v[64:79], v[124:127], v[92:95], 0
	v_add_u32_e32 v100, s8, v100
	v_mfma_f32_32x32x16_bf16 v[64:79], v[132:135], v[88:91], v[64:79]
	v_add_u32_e32 v102, s8, v102
	v_mfma_f32_32x32x16_bf16 v[64:79], v[136:139], v[84:87], v[64:79]
	v_add_u32_e32 v104, s8, v104
	v_mfma_f32_32x32x16_bf16 v[64:79], v[140:143], v[80:83], v[64:79]
	s_cbranch_scc1 .Ldt_d1_bias2

; #define SBAR() __builtin_amdgcn_sched_barrier(0)
; #define ATT_DMA_K(t) do { const bf16_t* kg_ = Kh + (size_t)(t) * 64 * LDK; LAS unsigned char* sb_ = lds + ((t) & 3) * KBUF; \
;     _Pragma("unroll") for (int i_ = 0; i_ < NKP; ++i_) __builtin_amdgcn_global_load_lds((const unsigned*)(kg_ + kgo[i_]), (LAS unsigned*)(sb_ + (wid + 8 * i_) * 1024), 16, 0, 0); } while (0)
; #define ATT_DMA_V(t, vs) do { const bf16_t* vg_ = Vh + (size_t)(t) * 64 * LDV; LAS unsigned char* sb_ = lds + V_OFF + (vs) * SHM_V; \
;     _Pragma("unroll") for (int i_ = 0; i_ < 2; ++i_) __builtin_amdgcn_global_load_lds((const unsigned*)(vg_ + vgo[i_]), (LAS unsigned*)(sb_ + (2 * wid + i_) * 1024), 16, 0, 0); } while (0)
; #define ATT_SEG(t) do { if constexpr (MODE != 0) { if (((t) == tL && tL > 0) || (t) == tR) { const float f_ = (t) == tR ? fR : fL; l_reg *= f_; \
;     _Pragma("unroll") for (int d = 0; d < 4; ++d) _Pragma("unroll") for (int r = 0; r < 16; ++r) o[d][r] *= f_; } } } while (0)
; #define ATT_BIAS(P, t, half) do { if constexpr (MODE != 0) { if ((t) >= tL && (t) < tR) { const LAS float* bp_ = bt + ((t) * 64 + (half) * 32 - qpos + 224 + 4 * hi);     \
;     _Pragma("unroll") for (int r = 0; r < 16; ++r) P[r] += bp_[(r & 3) + 8 * (r >> 2)]; } } } while (0)
; #define ATT_TOP(N) do { asm volatile("s_waitcnt vmcnt(%0)" :: "n"(N) : "memory"); __builtin_amdgcn_s_barrier(); asm volatile("" ::: "memory"); } while (0)
; template <int DQK, int MODE, int LDQ, int LDK, int LDV> ...
;     ...
;     f32x16 pA, pB; bf16x8 pa0, pa1;
;     int v0 = 0, v1 = 1, v2 = 2;
;     ATT_TOP(NKP + 2);
;     { bf16x8 kf[NDA]; k_reads<DQK, 0, NDA>(kf, lds, 0, r32, hi); ATT_LGKM0(); qk_mma<0, NDA>(pA, kf, qr);
;       if constexpr (ND0 > NDA) { bf16x8 kg[ND0 - NDA]; k_reads<DQK, NDA, ND0>(kg, lds, 0, r32, hi); ATT_LGKM0(); qk_mma<NDA, ND0>(pA, kg, qr); }
;       ATT_BIAS(pA, 0, 0); }
;     if (wid >= 4) __builtin_amdgcn_s_setprio(1);
;     for (int j = 0; j < NT; ++j) {
;         if (j + 2 < NT) ATT_TOP(NKP + 2); else ATT_TOP(0);
;         if (j + 3 < NT) ATT_DMA_K(j + 3);
;         if (j + 2 < NT) ATT_DMA_V(j + 2, v2);
;         ATT_SEG(j); SBAR();
;         ATT_STEP(pA, pB, 0, v0, true, 1, j);
;         ATT_STEP(pB, pA, 1, v0, (j + 1 < NT), 0, j + 1);
;         { const int t_ = v0; v0 = v1; v1 = v2; v2 = t_; }
;     }
.Lhw_mla_b_n1982:
	s_and_b32 s1, s43, 3
	s_mulk_i32 s1, 0x6000
	s_add_i32 s1, s49, s1
	s_setprio 0
	s_mov_b32 m0, s1
	s_mov_b32 s0, s5
	s_mov_b32 s5, s44
	s_mov_b32 s44, s4
	s_lshl_b32 s4, s4, 14
	global_load_lds_dwordx4 v136, s[34:35]
	s_add_i32 m0, s1, 0x2000
	s_add_i32 s4, s52, s4
	global_load_lds_dwordx4 v138, s[34:35]
	s_add_i32 m0, s1, 0x4000
	s_add_i32 s6, s4, 0x400
	global_load_lds_dwordx4 v140, s[34:35]
	s_mov_b32 m0, s4
	s_add_i32 s1, s43, -3
	global_load_lds_dwordx4 v144, s[34:35]
	s_mov_b32 m0, s6
	s_nop 0
	global_load_lds_dwordx4 v142, s[34:35]
	s_and_b32 s1, s1, 3
	s_mulk_i32 s1, 0x6000
	v_add_u32_e32 v246, s1, v158
	v_add_u32_e32 v250, v246, v151
	v_add_u32_e32 v251, v246, v149
	v_add_u32_e32 v252, v246, v148
	v_add_u32_e32 v253, v246, v147
	s_lshl_b32 s1, s0, 14
	ds_read_b128 v[190:193], v250 offset:12416
	ds_read_b128 v[194:197], v251 offset:12416
	ds_read_b128 v[174:177], v250 offset:12288
	ds_read_b128 v[178:181], v251 offset:12288
	ds_read_b128 v[182:185], v252 offset:12288
	ds_read_b128 v[186:189], v253 offset:12288
	v_add_u32_e32 v254, s1, v130
	ds_read_b64_tr_b16 v[198:199], v254 offset:0
	ds_read_b64_tr_b16 v[200:201], v254 offset:0x800
	ds_read_b64_tr_b16 v[202:203], v254 offset:0x1000
	ds_read_b64_tr_b16 v[204:205], v254 offset:0x1800
	ds_read_b64_tr_b16 v[206:207], v254 offset:0x200
	ds_read_b64_tr_b16 v[208:209], v254 offset:0xa00
	ds_read_b64_tr_b16 v[210:211], v254 offset:0x1200
	ds_read_b64_tr_b16 v[212:213], v254 offset:0x1a00
	ds_read_b64_tr_b16 v[214:215], v254 offset:0x400
	ds_read_b64_tr_b16 v[216:217], v254 offset:0xc00
	ds_read_b64_tr_b16 v[218:219], v254 offset:0x1400
	ds_read_b64_tr_b16 v[220:221], v254 offset:0x1c00
	ds_read_b64_tr_b16 v[222:223], v254 offset:0x600
	ds_read_b64_tr_b16 v[224:225], v254 offset:0xe00
	ds_read_b64_tr_b16 v[226:227], v254 offset:0x1600
	ds_read_b64_tr_b16 v[228:229], v254 offset:0x1e00
	s_setprio 2
	v_exp_f32_e32 v64, v64
	v_exp_f32_e32 v65, v65
	v_exp_f32_e32 v66, v66
	v_exp_f32_e32 v67, v67
	v_exp_f32_e32 v68, v68
	v_exp_f32_e32 v69, v69
	v_add_f32_e32 v230, v65, v64
	v_exp_f32_e32 v70, v70
	v_add_f32_e32 v230, v66, v230
	v_exp_f32_e32 v71, v71
	v_add_f32_e32 v230, v67, v230
	v_exp_f32_e32 v72, v72
	v_add_f32_e32 v230, v68, v230
	v_exp_f32_e32 v73, v73
	v_add_f32_e32 v230, v69, v230
	v_exp_f32_e32 v74, v74
	v_add_f32_e32 v230, v70, v230
	v_exp_f32_e32 v75, v75
	v_add_f32_e32 v230, v71, v230
	v_exp_f32_e32 v76, v76
	v_add_f32_e32 v230, v72, v230
	v_exp_f32_e32 v77, v77
	v_add_f32_e32 v230, v73, v230
	v_exp_f32_e32 v78, v78
	v_add_f32_e32 v230, v74, v230
	v_exp_f32_e32 v79, v79
	v_add_f32_e32 v230, v75, v230
	v_add_f32_e32 v230, v76, v230
	v_add_f32_e32 v230, v77, v230
	v_add_f32_e32 v230, v78, v230
	v_add_f32_e32 v230, v79, v230
	v_add_f32_e32 v173, v173, v230
	v_cvt_pk_bf16_f32 v64, v64, v65
	v_cvt_pk_bf16_f32 v65, v66, v67
	v_cvt_pk_bf16_f32 v66, v68, v69
	v_cvt_pk_bf16_f32 v67, v70, v71
	v_cvt_pk_bf16_f32 v68, v72, v73
	v_cvt_pk_bf16_f32 v69, v74, v75
	v_cvt_pk_bf16_f32 v70, v76, v77
	v_cvt_pk_bf16_f32 v71, v78, v79
	s_waitcnt lgkmcnt(0)
	ds_read_b128 v[230:233], v252 offset:12416
	ds_read_b128 v[234:237], v253 offset:12416
	ds_read_b128 v[238:241], v250 offset:12544
	ds_read_b128 v[242:245], v251 offset:12544
	ds_read_b128 v[246:249], v252 offset:12544
	ds_read_b128 v[250:253], v253 offset:12544
	s_setprio 3
	v_mfma_f32_32x32x16_bf16 v[48:63], v[64:67], v[198:201], v[48:63]
	v_mfma_f32_32x32x16_bf16 v[32:47], v[64:67], v[206:209], v[32:47]
	v_mfma_f32_32x32x16_bf16 v[16:31], v[64:67], v[214:217], v[16:31]
	v_mfma_f32_32x32x16_bf16 v[0:15], v[64:67], v[222:225], v[0:15]
	v_mfma_f32_32x32x16_bf16 v[48:63], v[68:71], v[202:205], v[48:63]
	v_mfma_f32_32x32x16_bf16 v[32:47], v[68:71], v[210:213], v[32:47]
	v_mfma_f32_32x32x16_bf16 v[16:31], v[68:71], v[218:221], v[16:31]
	v_mfma_f32_32x32x16_bf16 v[0:15], v[68:71], v[226:229], v[0:15]
	s_waitcnt lgkmcnt(0)
	v_mfma_f32_32x32x16_bf16 v[64:79], v[174:177], v[80:83], 0
	v_mfma_f32_32x32x16_bf16 v[64:79], v[178:181], v[84:87], v[64:79]
	v_mfma_f32_32x32x16_bf16 v[64:79], v[182:185], v[88:91], v[64:79]
	v_mfma_f32_32x32x16_bf16 v[64:79], v[186:189], v[92:95], v[64:79]
	v_mfma_f32_32x32x16_bf16 v[64:79], v[190:193], v[96:99], v[64:79]
	v_mfma_f32_32x32x16_bf16 v[64:79], v[194:197], v[100:103], v[64:79]
	v_mfma_f32_32x32x16_bf16 v[64:79], v[230:233], v[104:107], v[64:79]
	v_mfma_f32_32x32x16_bf16 v[64:79], v[234:237], v[108:111], v[64:79]
	v_mfma_f32_32x32x16_bf16 v[64:79], v[238:241], v[112:115], v[64:79]
	v_mfma_f32_32x32x16_bf16 v[64:79], v[242:245], v[116:119], v[64:79]
	v_mfma_f32_32x32x16_bf16 v[64:79], v[246:249], v[120:123], v[64:79]
	v_mfma_f32_32x32x16_bf16 v[64:79], v[250:253], v[124:127], v[64:79]
	s_setprio 0
	s_add_i32 s4, s43, -2
	s_and_b32 s4, s4, 3
	s_mulk_i32 s4, 0x6000
	v_add_u32_e32 v246, s4, v158
	v_add_u32_e32 v250, v246, v151
	v_add_u32_e32 v251, v246, v149
	v_add_u32_e32 v252, v246, v148
	v_add_u32_e32 v253, v246, v147
	ds_read_b128 v[190:193], v250 offset:128
	ds_read_b128 v[194:197], v251 offset:128
	ds_read_b128 v[174:177], v250
	ds_read_b128 v[178:181], v251
	ds_read_b128 v[182:185], v252
	ds_read_b128 v[186:189], v253
	ds_read_b64_tr_b16 v[198:199], v254 offset:0x2000
	ds_read_b64_tr_b16 v[200:201], v254 offset:0x2800
	ds_read_b64_tr_b16 v[202:203], v254 offset:0x3000
	ds_read_b64_tr_b16 v[204:205], v254 offset:0x3800
	ds_read_b64_tr_b16 v[206:207], v254 offset:0x2200
	ds_read_b64_tr_b16 v[208:209], v254 offset:0x2a00
	ds_read_b64_tr_b16 v[210:211], v254 offset:0x3200
	ds_read_b64_tr_b16 v[212:213], v254 offset:0x3a00
	ds_read_b64_tr_b16 v[214:215], v254 offset:0x2400
	ds_read_b64_tr_b16 v[216:217], v254 offset:0x2c00
; #define SBAR() __builtin_amdgcn_sched_barrier(0)
; #define ATT_DMA_K(t) do { const bf16_t* kg_ = Kh + (size_t)(t) * 64 * LDK; LAS unsigned char* sb_ = lds + ((t) & 3) * KBUF; \
;     _Pragma("unroll") for (int i_ = 0; i_ < NKP; ++i_) __builtin_amdgcn_global_load_lds((const unsigned*)(kg_ + kgo[i_]), (LAS unsigned*)(sb_ + (wid + 8 * i_) * 1024), 16, 0, 0); } while (0)
; #define ATT_DMA_V(t, vs) do { const bf16_t* vg_ = Vh + (size_t)(t) * 64 * LDV; LAS unsigned char* sb_ = lds + V_OFF + (vs) * SHM_V; \
;     _Pragma("unroll") for (int i_ = 0; i_ < 2; ++i_) __builtin_amdgcn_global_load_lds((const unsigned*)(vg_ + vgo[i_]), (LAS unsigned*)(sb_ + (2 * wid + i_) * 1024), 16, 0, 0); } while (0)
; #define ATT_SEG(t) do { if constexpr (MODE != 0) { if (((t) == tL && tL > 0) || (t) == tR) { const float f_ = (t) == tR ? fR : fL; l_reg *= f_; \
;     _Pragma("unroll") for (int d = 0; d < 4; ++d) _Pragma("unroll") for (int r = 0; r < 16; ++r) o[d][r] *= f_; } } } while (0)
; #define ATT_BIAS(P, t, half) do { if constexpr (MODE != 0) { if ((t) >= tL && (t) < tR) { const LAS float* bp_ = bt + ((t) * 64 + (half) * 32 - qpos + 224 + 4 * hi);     \
;     _Pragma("unroll") for (int r = 0; r < 16; ++r) P[r] += bp_[(r & 3) + 8 * (r >> 2)]; } } } while (0)
; #define ATT_TOP(N) do { asm volatile("s_waitcnt vmcnt(%0)" :: "n"(N) : "memory"); __builtin_amdgcn_s_barrier(); asm volatile("" ::: "memory"); } while (0)
; template <int DQK, int MODE, int LDQ, int LDK, int LDV> ...
;     ...
;     f32x16 pA, pB; bf16x8 pa0, pa1;
;     int v0 = 0, v1 = 1, v2 = 2;
;     ATT_TOP(NKP + 2);
;     { bf16x8 kf[NDA]; k_reads<DQK, 0, NDA>(kf, lds, 0, r32, hi); ATT_LGKM0(); qk_mma<0, NDA>(pA, kf, qr);
;       if constexpr (ND0 > NDA) { bf16x8 kg[ND0 - NDA]; k_reads<DQK, NDA, ND0>(kg, lds, 0, r32, hi); ATT_LGKM0(); qk_mma<NDA, ND0>(pA, kg, qr); }
;       ATT_BIAS(pA, 0, 0); }
;     if (wid >= 4) __builtin_amdgcn_s_setprio(1);
;     for (int j = 0; j < NT; ++j) {
;         if (j + 2 < NT) ATT_TOP(NKP + 2); else ATT_TOP(0);
;         if (j + 3 < NT) ATT_DMA_K(j + 3);
;         if (j + 2 < NT) ATT_DMA_V(j + 2, v2);
;         ATT_SEG(j); SBAR();
;         ATT_STEP(pA, pB, 0, v0, true, 1, j);
;         ATT_STEP(pB, pA, 1, v0, (j + 1 < NT), 0, j + 1);
;         { const int t_ = v0; v0 = v1; v1 = v2; v2 = t_; }
;     }
	ds_read_b64_tr_b16 v[218:219], v254 offset:0x3400
	ds_read_b64_tr_b16 v[220:221], v254 offset:0x3c00
	ds_read_b64_tr_b16 v[222:223], v254 offset:0x2600
	ds_read_b64_tr_b16 v[224:225], v254 offset:0x2e00
	ds_read_b64_tr_b16 v[226:227], v254 offset:0x3600
	ds_read_b64_tr_b16 v[228:229], v254 offset:0x3e00
	s_setprio 2
	v_exp_f32_e32 v64, v64
	v_exp_f32_e32 v65, v65
	v_exp_f32_e32 v66, v66
	v_exp_f32_e32 v67, v67
	v_exp_f32_e32 v68, v68
	v_exp_f32_e32 v69, v69
	v_add_f32_e32 v230, v65, v64
	v_exp_f32_e32 v70, v70
	v_add_f32_e32 v230, v66, v230
	v_exp_f32_e32 v71, v71
	v_add_f32_e32 v230, v67, v230
	v_exp_f32_e32 v72, v72
	v_add_f32_e32 v230, v68, v230
	v_exp_f32_e32 v73, v73
	v_add_f32_e32 v230, v69, v230
	v_exp_f32_e32 v74, v74
	v_add_f32_e32 v230, v70, v230
	v_exp_f32_e32 v75, v75
	v_add_f32_e32 v230, v71, v230
	v_exp_f32_e32 v76, v76
	v_add_f32_e32 v230, v72, v230
	v_exp_f32_e32 v77, v77
	v_add_f32_e32 v230, v73, v230
	v_exp_f32_e32 v78, v78
	v_add_f32_e32 v230, v74, v230
	v_exp_f32_e32 v79, v79
	v_add_f32_e32 v230, v75, v230
	v_add_f32_e32 v230, v76, v230
	v_add_f32_e32 v230, v77, v230
	v_add_f32_e32 v230, v78, v230
	v_add_f32_e32 v230, v79, v230
	v_add_f32_e32 v173, v173, v230
	v_cvt_pk_bf16_f32 v64, v64, v65
	v_cvt_pk_bf16_f32 v65, v66, v67
	v_cvt_pk_bf16_f32 v66, v68, v69
	v_cvt_pk_bf16_f32 v67, v70, v71
	v_cvt_pk_bf16_f32 v68, v72, v73
	v_cvt_pk_bf16_f32 v69, v74, v75
	v_cvt_pk_bf16_f32 v70, v76, v77
	v_cvt_pk_bf16_f32 v71, v78, v79
	s_waitcnt lgkmcnt(0)
	ds_read_b128 v[230:233], v252 offset:128
	ds_read_b128 v[234:237], v253 offset:128
	ds_read_b128 v[238:241], v250 offset:256
	ds_read_b128 v[242:245], v251 offset:256
	ds_read_b128 v[246:249], v252 offset:256
	ds_read_b128 v[250:253], v253 offset:256
	s_setprio 3
	s_waitcnt vmcnt(5)
	s_barrier
	v_mfma_f32_32x32x16_bf16 v[48:63], v[64:67], v[198:201], v[48:63]
	v_mfma_f32_32x32x16_bf16 v[32:47], v[64:67], v[206:209], v[32:47]
	v_mfma_f32_32x32x16_bf16 v[16:31], v[64:67], v[214:217], v[16:31]
	v_mfma_f32_32x32x16_bf16 v[0:15], v[64:67], v[222:225], v[0:15]
	v_mfma_f32_32x32x16_bf16 v[48:63], v[68:71], v[202:205], v[48:63]
	v_mfma_f32_32x32x16_bf16 v[32:47], v[68:71], v[210:213], v[32:47]
	v_mfma_f32_32x32x16_bf16 v[16:31], v[68:71], v[218:221], v[16:31]
	v_mfma_f32_32x32x16_bf16 v[0:15], v[68:71], v[226:229], v[0:15]
	s_waitcnt lgkmcnt(0)
	v_mfma_f32_32x32x16_bf16 v[64:79], v[174:177], v[80:83], 0
	v_mfma_f32_32x32x16_bf16 v[64:79], v[178:181], v[84:87], v[64:79]
	v_mfma_f32_32x32x16_bf16 v[64:79], v[182:185], v[88:91], v[64:79]
	v_mfma_f32_32x32x16_bf16 v[64:79], v[186:189], v[92:95], v[64:79]
	v_mfma_f32_32x32x16_bf16 v[64:79], v[190:193], v[96:99], v[64:79]
	v_mfma_f32_32x32x16_bf16 v[64:79], v[194:197], v[100:103], v[64:79]
	v_mfma_f32_32x32x16_bf16 v[64:79], v[230:233], v[104:107], v[64:79]
	v_mfma_f32_32x32x16_bf16 v[64:79], v[234:237], v[108:111], v[64:79]
	v_mfma_f32_32x32x16_bf16 v[64:79], v[238:241], v[112:115], v[64:79]
	v_mfma_f32_32x32x16_bf16 v[64:79], v[242:245], v[116:119], v[64:79]
	v_mfma_f32_32x32x16_bf16 v[64:79], v[246:249], v[120:123], v[64:79]
	v_mfma_f32_32x32x16_bf16 v[64:79], v[250:253], v[124:127], v[64:79]
	s_add_i32 s43, s43, 1
	v_add_u32_e32 v136, s36, v136
	v_add_u32_e32 v138, s36, v138
	v_add_u32_e32 v140, s36, v140
	v_add_u32_e32 v142, s38, v142
	v_add_u32_e32 v144, s38, v144
	s_cmp_eq_u32 s43, 64
	s_mov_b32 s4, s0
	s_cbranch_scc0 .Lhw_mla_b_n1982
	s_branch .Lhw_mla_exit
.LBB0_1982:
	s_and_b32 s1, s43, 3
	s_mulk_i32 s1, 0x6000
	s_add_i32 s1, s49, s1
	s_waitcnt vmcnt(5)
	s_barrier
	s_setprio 0
	s_mov_b32 m0, s1
	s_mov_b32 s0, s5
	s_mov_b32 s5, s44
	s_mov_b32 s44, s4
	s_lshl_b32 s4, s4, 14
	global_load_lds_dwordx4 v136, s[34:35]
	s_add_i32 m0, s1, 0x2000
	s_add_i32 s4, s52, s4
	global_load_lds_dwordx4 v138, s[34:35]
	s_add_i32 m0, s1, 0x4000
	s_add_i32 s6, s4, 0x400
	global_load_lds_dwordx4 v140, s[34:35]
	s_mov_b32 m0, s4
	s_add_i32 s1, s43, -3
	global_load_lds_dwordx4 v144, s[34:35]
	s_mov_b32 m0, s6
	s_nop 0
	global_load_lds_dwordx4 v142, s[34:35]
	s_and_b32 s1, s1, 3
	s_mulk_i32 s1, 0x6000
	v_add_u32_e32 v246, s1, v158
	v_add_u32_e32 v250, v246, v151
	v_add_u32_e32 v251, v246, v149
	v_add_u32_e32 v252, v246, v148
	v_add_u32_e32 v253, v246, v147
	s_lshl_b32 s1, s0, 14
	ds_read_b128 v[190:193], v250 offset:12416
	ds_read_b128 v[194:197], v251 offset:12416
	ds_read_b128 v[174:177], v250 offset:12288
	ds_read_b128 v[178:181], v251 offset:12288
	ds_read_b128 v[182:185], v252 offset:12288
	ds_read_b128 v[186:189], v253 offset:12288
	v_add_u32_e32 v254, s1, v130
	ds_read_b64_tr_b16 v[198:199], v254 offset:0
	ds_read_b64_tr_b16 v[200:201], v254 offset:0x800
	ds_read_b64_tr_b16 v[202:203], v254 offset:0x1000
	ds_read_b64_tr_b16 v[204:205], v254 offset:0x1800
	ds_read_b64_tr_b16 v[206:207], v254 offset:0x200
	ds_read_b64_tr_b16 v[208:209], v254 offset:0xa00
	ds_read_b64_tr_b16 v[210:211], v254 offset:0x1200
	ds_read_b64_tr_b16 v[212:213], v254 offset:0x1a00
	ds_read_b64_tr_b16 v[214:215], v254 offset:0x400
	ds_read_b64_tr_b16 v[216:217], v254 offset:0xc00
	ds_read_b64_tr_b16 v[218:219], v254 offset:0x1400
	ds_read_b64_tr_b16 v[220:221], v254 offset:0x1c00
	ds_read_b64_tr_b16 v[222:223], v254 offset:0x600
	ds_read_b64_tr_b16 v[224:225], v254 offset:0xe00
	ds_read_b64_tr_b16 v[226:227], v254 offset:0x1600
	ds_read_b64_tr_b16 v[228:229], v254 offset:0x1e00
	s_setprio 1
	v_exp_f32_e32 v64, v64
	v_exp_f32_e32 v65, v65
	v_exp_f32_e32 v66, v66
	v_exp_f32_e32 v67, v67
	v_exp_f32_e32 v68, v68
	v_exp_f32_e32 v69, v69
	v_add_f32_e32 v230, v65, v64
	v_exp_f32_e32 v70, v70
	v_add_f32_e32 v230, v66, v230
	v_exp_f32_e32 v71, v71
	v_add_f32_e32 v230, v67, v230
	v_exp_f32_e32 v72, v72
	v_add_f32_e32 v230, v68, v230
	v_exp_f32_e32 v73, v73
	v_add_f32_e32 v230, v69, v230
	v_exp_f32_e32 v74, v74
	v_add_f32_e32 v230, v70, v230
	v_exp_f32_e32 v75, v75
	v_add_f32_e32 v230, v71, v230
	v_exp_f32_e32 v76, v76
	v_add_f32_e32 v230, v72, v230
	v_exp_f32_e32 v77, v77
	v_add_f32_e32 v230, v73, v230
	v_exp_f32_e32 v78, v78
	v_add_f32_e32 v230, v74, v230
	v_exp_f32_e32 v79, v79
	v_add_f32_e32 v230, v75, v230
	v_add_f32_e32 v230, v76, v230
	v_add_f32_e32 v230, v77, v230
	v_add_f32_e32 v230, v78, v230
	v_add_f32_e32 v230, v79, v230
	v_add_f32_e32 v173, v173, v230
	v_cvt_pk_bf16_f32 v64, v64, v65
	v_cvt_pk_bf16_f32 v65, v66, v67
	v_cvt_pk_bf16_f32 v66, v68, v69
	v_cvt_pk_bf16_f32 v67, v70, v71
	v_cvt_pk_bf16_f32 v68, v72, v73
	v_cvt_pk_bf16_f32 v69, v74, v75
	v_cvt_pk_bf16_f32 v70, v76, v77
	v_cvt_pk_bf16_f32 v71, v78, v79
	s_waitcnt lgkmcnt(0)
; #define SBAR() __builtin_amdgcn_sched_barrier(0)
; #define ATT_DMA_K(t) do { const bf16_t* kg_ = Kh + (size_t)(t) * 64 * LDK; LAS unsigned char* sb_ = lds + ((t) & 3) * KBUF; \
;     _Pragma("unroll") for (int i_ = 0; i_ < NKP; ++i_) __builtin_amdgcn_global_load_lds((const unsigned*)(kg_ + kgo[i_]), (LAS unsigned*)(sb_ + (wid + 8 * i_) * 1024), 16, 0, 0); } while (0)
; #define ATT_DMA_V(t, vs) do { const bf16_t* vg_ = Vh + (size_t)(t) * 64 * LDV; LAS unsigned char* sb_ = lds + V_OFF + (vs) * SHM_V; \
;     _Pragma("unroll") for (int i_ = 0; i_ < 2; ++i_) __builtin_amdgcn_global_load_lds((const unsigned*)(vg_ + vgo[i_]), (LAS unsigned*)(sb_ + (2 * wid + i_) * 1024), 16, 0, 0); } while (0)
; #define ATT_SEG(t) do { if constexpr (MODE != 0) { if (((t) == tL && tL > 0) || (t) == tR) { const float f_ = (t) == tR ? fR : fL; l_reg *= f_; \
;     _Pragma("unroll") for (int d = 0; d < 4; ++d) _Pragma("unroll") for (int r = 0; r < 16; ++r) o[d][r] *= f_; } } } while (0)
; #define ATT_BIAS(P, t, half) do { if constexpr (MODE != 0) { if ((t) >= tL && (t) < tR) { const LAS float* bp_ = bt + ((t) * 64 + (half) * 32 - qpos + 224 + 4 * hi);     \
;     _Pragma("unroll") for (int r = 0; r < 16; ++r) P[r] += bp_[(r & 3) + 8 * (r >> 2)]; } } } while (0)
; #define ATT_TOP(N) do { asm volatile("s_waitcnt vmcnt(%0)" :: "n"(N) : "memory"); __builtin_amdgcn_s_barrier(); asm volatile("" ::: "memory"); } while (0)
; template <int DQK, int MODE, int LDQ, int LDK, int LDV> ...
;     ...
;     f32x16 pA, pB; bf16x8 pa0, pa1;
;     int v0 = 0, v1 = 1, v2 = 2;
;     ATT_TOP(NKP + 2);
;     { bf16x8 kf[NDA]; k_reads<DQK, 0, NDA>(kf, lds, 0, r32, hi); ATT_LGKM0(); qk_mma<0, NDA>(pA, kf, qr);
;       if constexpr (ND0 > NDA) { bf16x8 kg[ND0 - NDA]; k_reads<DQK, NDA, ND0>(kg, lds, 0, r32, hi); ATT_LGKM0(); qk_mma<NDA, ND0>(pA, kg, qr); }
;       ATT_BIAS(pA, 0, 0); }
;     if (wid >= 4) __builtin_amdgcn_s_setprio(1);
;     for (int j = 0; j < NT; ++j) {
;         if (j + 2 < NT) ATT_TOP(NKP + 2); else ATT_TOP(0);
;         if (j + 3 < NT) ATT_DMA_K(j + 3);
;         if (j + 2 < NT) ATT_DMA_V(j + 2, v2);
;         ATT_SEG(j); SBAR();
;         ATT_STEP(pA, pB, 0, v0, true, 1, j);
;         ATT_STEP(pB, pA, 1, v0, (j + 1 < NT), 0, j + 1);
;         { const int t_ = v0; v0 = v1; v1 = v2; v2 = t_; }
;     }
	ds_read_b128 v[230:233], v252 offset:12416
	ds_read_b128 v[234:237], v253 offset:12416
	ds_read_b128 v[238:241], v250 offset:12544
	ds_read_b128 v[242:245], v251 offset:12544
	ds_read_b128 v[246:249], v252 offset:12544
	ds_read_b128 v[250:253], v253 offset:12544
	s_setprio 3
	v_mfma_f32_32x32x16_bf16 v[48:63], v[64:67], v[198:201], v[48:63]
	v_mfma_f32_32x32x16_bf16 v[32:47], v[64:67], v[206:209], v[32:47]
	v_mfma_f32_32x32x16_bf16 v[16:31], v[64:67], v[214:217], v[16:31]
	v_mfma_f32_32x32x16_bf16 v[0:15], v[64:67], v[222:225], v[0:15]
	v_mfma_f32_32x32x16_bf16 v[48:63], v[68:71], v[202:205], v[48:63]
	v_mfma_f32_32x32x16_bf16 v[32:47], v[68:71], v[210:213], v[32:47]
	v_mfma_f32_32x32x16_bf16 v[16:31], v[68:71], v[218:221], v[16:31]
	v_mfma_f32_32x32x16_bf16 v[0:15], v[68:71], v[226:229], v[0:15]
	s_waitcnt lgkmcnt(0)
	v_mfma_f32_32x32x16_bf16 v[64:79], v[174:177], v[80:83], 0
	v_mfma_f32_32x32x16_bf16 v[64:79], v[178:181], v[84:87], v[64:79]
	v_mfma_f32_32x32x16_bf16 v[64:79], v[182:185], v[88:91], v[64:79]
	v_mfma_f32_32x32x16_bf16 v[64:79], v[186:189], v[92:95], v[64:79]
	v_mfma_f32_32x32x16_bf16 v[64:79], v[190:193], v[96:99], v[64:79]
	v_mfma_f32_32x32x16_bf16 v[64:79], v[194:197], v[100:103], v[64:79]
	v_mfma_f32_32x32x16_bf16 v[64:79], v[230:233], v[104:107], v[64:79]
	v_mfma_f32_32x32x16_bf16 v[64:79], v[234:237], v[108:111], v[64:79]
	v_mfma_f32_32x32x16_bf16 v[64:79], v[238:241], v[112:115], v[64:79]
	v_mfma_f32_32x32x16_bf16 v[64:79], v[242:245], v[116:119], v[64:79]
	v_mfma_f32_32x32x16_bf16 v[64:79], v[246:249], v[120:123], v[64:79]
	v_mfma_f32_32x32x16_bf16 v[64:79], v[250:253], v[124:127], v[64:79]
	s_setprio 0
	s_add_i32 s4, s43, -2
	s_and_b32 s4, s4, 3
	s_mulk_i32 s4, 0x6000
	v_add_u32_e32 v246, s4, v158
	v_add_u32_e32 v250, v246, v151
	v_add_u32_e32 v251, v246, v149
	v_add_u32_e32 v252, v246, v148
	v_add_u32_e32 v253, v246, v147
	ds_read_b128 v[190:193], v250 offset:128
	ds_read_b128 v[194:197], v251 offset:128
	ds_read_b128 v[174:177], v250
	ds_read_b128 v[178:181], v251
	ds_read_b128 v[182:185], v252
	ds_read_b128 v[186:189], v253
	ds_read_b64_tr_b16 v[198:199], v254 offset:0x2000
	ds_read_b64_tr_b16 v[200:201], v254 offset:0x2800
	ds_read_b64_tr_b16 v[202:203], v254 offset:0x3000
	ds_read_b64_tr_b16 v[204:205], v254 offset:0x3800
	ds_read_b64_tr_b16 v[206:207], v254 offset:0x2200
	ds_read_b64_tr_b16 v[208:209], v254 offset:0x2a00
	ds_read_b64_tr_b16 v[210:211], v254 offset:0x3200
	ds_read_b64_tr_b16 v[212:213], v254 offset:0x3a00
	ds_read_b64_tr_b16 v[214:215], v254 offset:0x2400
	ds_read_b64_tr_b16 v[216:217], v254 offset:0x2c00
	ds_read_b64_tr_b16 v[218:219], v254 offset:0x3400
	ds_read_b64_tr_b16 v[220:221], v254 offset:0x3c00
	ds_read_b64_tr_b16 v[222:223], v254 offset:0x2600
	ds_read_b64_tr_b16 v[224:225], v254 offset:0x2e00
	ds_read_b64_tr_b16 v[226:227], v254 offset:0x3600
	ds_read_b64_tr_b16 v[228:229], v254 offset:0x3e00
	s_setprio 1
	v_exp_f32_e32 v64, v64
	v_exp_f32_e32 v65, v65
	v_exp_f32_e32 v66, v66
	v_exp_f32_e32 v67, v67
	v_exp_f32_e32 v68, v68
	v_exp_f32_e32 v69, v69
	v_add_f32_e32 v230, v65, v64
	v_exp_f32_e32 v70, v70
	v_add_f32_e32 v230, v66, v230
	v_exp_f32_e32 v71, v71
	v_add_f32_e32 v230, v67, v230
	v_exp_f32_e32 v72, v72
	v_add_f32_e32 v230, v68, v230
	v_exp_f32_e32 v73, v73
	v_add_f32_e32 v230, v69, v230
	v_exp_f32_e32 v74, v74
	v_add_f32_e32 v230, v70, v230
	v_exp_f32_e32 v75, v75
	v_add_f32_e32 v230, v71, v230
	v_exp_f32_e32 v76, v76
	v_add_f32_e32 v230, v72, v230
	v_exp_f32_e32 v77, v77
	v_add_f32_e32 v230, v73, v230
	v_exp_f32_e32 v78, v78
	v_add_f32_e32 v230, v74, v230
	v_exp_f32_e32 v79, v79
	v_add_f32_e32 v230, v75, v230
	v_add_f32_e32 v230, v76, v230
	v_add_f32_e32 v230, v77, v230
	v_add_f32_e32 v230, v78, v230
	v_add_f32_e32 v230, v79, v230
	v_add_f32_e32 v173, v173, v230
	v_cvt_pk_bf16_f32 v64, v64, v65
	v_cvt_pk_bf16_f32 v65, v66, v67
	v_cvt_pk_bf16_f32 v66, v68, v69
	v_cvt_pk_bf16_f32 v67, v70, v71
	v_cvt_pk_bf16_f32 v68, v72, v73
	v_cvt_pk_bf16_f32 v69, v74, v75
	v_cvt_pk_bf16_f32 v70, v76, v77
	v_cvt_pk_bf16_f32 v71, v78, v79
	s_waitcnt lgkmcnt(0)
	ds_read_b128 v[230:233], v252 offset:128
	ds_read_b128 v[234:237], v253 offset:128
	ds_read_b128 v[238:241], v250 offset:256
	ds_read_b128 v[242:245], v251 offset:256
	ds_read_b128 v[246:249], v252 offset:256
	ds_read_b128 v[250:253], v253 offset:256
	s_setprio 3
	v_mfma_f32_32x32x16_bf16 v[48:63], v[64:67], v[198:201], v[48:63]
	v_mfma_f32_32x32x16_bf16 v[32:47], v[64:67], v[206:209], v[32:47]
	v_mfma_f32_32x32x16_bf16 v[16:31], v[64:67], v[214:217], v[16:31]
	v_mfma_f32_32x32x16_bf16 v[0:15], v[64:67], v[222:225], v[0:15]
	v_mfma_f32_32x32x16_bf16 v[48:63], v[68:71], v[202:205], v[48:63]
	v_mfma_f32_32x32x16_bf16 v[32:47], v[68:71], v[210:213], v[32:47]
	v_mfma_f32_32x32x16_bf16 v[16:31], v[68:71], v[218:221], v[16:31]
	v_mfma_f32_32x32x16_bf16 v[0:15], v[68:71], v[226:229], v[0:15]
	s_waitcnt lgkmcnt(0)
	v_mfma_f32_32x32x16_bf16 v[64:79], v[174:177], v[80:83], 0
	v_mfma_f32_32x32x16_bf16 v[64:79], v[178:181], v[84:87], v[64:79]
	v_mfma_f32_32x32x16_bf16 v[64:79], v[182:185], v[88:91], v[64:79]
	v_mfma_f32_32x32x16_bf16 v[64:79], v[186:189], v[92:95], v[64:79]
	v_mfma_f32_32x32x16_bf16 v[64:79], v[190:193], v[96:99], v[64:79]
	v_mfma_f32_32x32x16_bf16 v[64:79], v[194:197], v[100:103], v[64:79]
	v_mfma_f32_32x32x16_bf16 v[64:79], v[230:233], v[104:107], v[64:79]
	v_mfma_f32_32x32x16_bf16 v[64:79], v[234:237], v[108:111], v[64:79]
	v_mfma_f32_32x32x16_bf16 v[64:79], v[238:241], v[112:115], v[64:79]
	v_mfma_f32_32x32x16_bf16 v[64:79], v[242:245], v[116:119], v[64:79]
	v_mfma_f32_32x32x16_bf16 v[64:79], v[246:249], v[120:123], v[64:79]
	v_mfma_f32_32x32x16_bf16 v[64:79], v[250:253], v[124:127], v[64:79]
	s_add_i32 s43, s43, 1
	v_add_u32_e32 v136, s36, v136
	v_add_u32_e32 v138, s36, v138
	v_add_u32_e32 v140, s36, v140
	v_add_u32_e32 v142, s38, v142
	v_add_u32_e32 v144, s38, v144
	s_cmp_eq_u32 s43, 64
	s_mov_b32 s4, s0
	s_cbranch_scc0 .LBB0_1982
